# P10 epilogue: conv bias folded into the FMA chain, sigmoid log2e scale folded into the LDS-staged gate/val weights; attention unit prologue: cumsum slice staged after the K/V/Q issues
# speedup vs baseline: 1.1111x; 1.0046x over previous
.LBB0_506:
	s_ashr_i32 s4, s0, 2
	s_lshl_b32 s0, s0, 8
	s_and_b32 s0, s0, 0x300
	s_and_b32 s5, s65, 1
	s_xor_b32 s26, s0, 0x700
	s_cmp_eq_u32 s5, 0
	v_mbcnt_lo_u32_b32 v252, -1, 0
	v_mbcnt_hi_u32_b32 v252, -1, v252
	s_cselect_b32 s52, s26, s0
	v_add_u32_e32 v2, s33, v252
	s_add_i32 s53, s52, 0x100
	v_lshlrev_b32_e32 v0, 2, v2
	v_readfirstlane_b32 s68, v2
	v_cmp_gt_i32_e32 vcc, s53, v0
	s_and_saveexec_b64 s[42:43], vcc
	s_mov_b64 s[100:101], exec
	s_cbranch_execz .LBB0_508
	s_ashr_i32 s5, s4, 31
	s_lshl_b64 s[26:27], s[4:5], 13
	s_add_u32 s26, s18, s26
	s_addc_u32 s27, s19, s27
	v_ashrrev_i32_e32 v1, 31, v0
	v_lshl_add_u64 v[0:1], v[0:1], 2, s[26:27]
	global_load_dwordx4 v[4:7], v[0:1], off
	v_lshl_add_u32 v8, v2, 4, 0
	v_add_u32_e32 v8, 0x14800, v8
.LBB0_508:
	s_or_b64 exec, exec, s[42:43]
	s_ashr_i32 s0, s4, 31
	s_lshr_b32 s0, s0, 29
	s_add_i32 s0, s4, s0
	s_ashr_i32 s26, s0, 3
	s_and_b32 s0, s0, -8
	s_ashr_i32 s45, s68, 6
	s_ashr_i32 s27, s26, 31
	s_sub_i32 s44, s4, s0
	s_lshl_b64 s[4:5], s[26:27], 11
	s_lshl_b32 s57, s45, 5
	s_or_b32 s0, s4, s52
	s_ashr_i32 s4, s57, 31
	s_add_u32 s42, s0, s57
	s_addc_u32 s43, s5, s4
	s_lshl_b64 s[4:5], s[42:43], 10
	s_add_u32 s0, s3, s4
	s_addc_u32 s54, s66, s5
	s_lshl_b32 s4, s44, 6
	s_ashr_i32 s5, s4, 31
	s_lshl_b64 s[50:51], s[4:5], 1
	s_add_u32 s4, s0, s50
	s_addc_u32 s5, s54, s51
	s_lshl_b64 s[26:27], s[26:27], 21
	s_add_u32 s0, s62, s26
	s_addc_u32 s55, s63, s27
	s_add_u32 s54, s0, s50
	s_addc_u32 s55, s55, s51
	s_add_u32 s0, s20, s26
	v_and_b32_e32 v253, 63, v252
	s_addc_u32 s27, s21, s27
	s_add_u32 s26, s0, s50
	v_lshlrev_b32_e32 v222, 10, v253
	s_addc_u32 s27, s27, s51
	v_lshl_add_u64 v[0:1], s[54:55], 0, v[222:223]
	s_lshl_b32 s54, s45, 3
	s_ashr_i32 s55, s54, 31
	v_lshl_add_u64 v[224:225], s[54:55], 1, v[0:1]
	s_lshl_b32 s0, s45, 4
	v_bfe_u32 v0, v252, 2, 4
	v_and_or_b32 v0, s0, 48, v0
	v_lshlrev_b32_e32 v222, 10, v0
	s_ashr_i32 s0, s68, 3
	v_lshl_add_u64 v[0:1], s[26:27], 0, v[222:223]
	s_and_b32 s26, s0, 0xffffffe0
	s_ashr_i32 s27, s26, 31
	s_lshl_b32 s56, s45, 10
	v_lshlrev_b32_e32 v2, 3, v252
	s_cmp_lg_u32 0, -1
	v_and_b32_e32 v240, 24, v2
	s_cselect_b32 s0, 0, 0
	v_lshl_add_u64 v[0:1], s[26:27], 1, v[0:1]
	v_lshlrev_b32_e32 v222, 1, v240
	s_add_i32 s69, s56, s0
	s_mov_b32 s0, m0
	s_mov_b32 m0, s69
	s_nop 0
	global_load_lds_dwordx4 v[224:225], off
	s_mov_b32 m0, s0
	v_and_b32_e32 v254, 31, v252
	v_lshl_add_u64 v[48:49], v[0:1], 0, v[222:223]
	s_add_i32 s70, s69, 0x6000
	s_mov_b32 s0, m0
	s_mov_b32 m0, s70
	s_nop 0
	global_load_lds_dwordx4 v[48:49], off
	s_mov_b32 m0, s0
	v_lshl_add_u64 v[0:1], v[224:225], 0, s[6:7]
	v_bfe_u32 v232, v252, 5, 1
	s_add_i32 s0, s69, 0x2000
	s_mov_b32 s26, m0
	s_mov_b32 m0, s0
	s_nop 0
	global_load_lds_dwordx4 v[0:1], off
	s_mov_b32 m0, s26
	v_lshlrev_b32_e32 v0, 10, v254
	v_lshl_or_b32 v2, v232, 4, v0
	global_load_dwordx4 v[140:143], v2, s[4:5] nt
	global_load_dwordx4 v[136:139], v2, s[4:5] offset:32 nt
	global_load_dwordx4 v[132:135], v2, s[4:5] offset:64 nt
	global_load_dwordx4 v[128:131], v2, s[4:5] offset:96 nt
	s_lshl_b32 s0, s52, 2
	s_add_i32 s67, s0, 0
	v_or_b32_e32 v239, s57, v254
	v_lshl_add_u64 v[0:1], v[224:225], 0, s[22:23]
	s_add_i32 s0, s69, 0x4000
	s_add_i32 s67, s67, 0x14800
	s_mov_b32 s4, m0
	s_mov_b32 m0, s0
	s_nop 0
	global_load_lds_dwordx4 v[0:1], off
	s_mov_b32 m0, s4
	v_lshl_add_u32 v3, v239, 2, s67
	s_waitcnt vmcnt(3)
	s_mov_b64 s[98:99], exec
	s_mov_b64 exec, s[100:101]
	ds_write_b128 v8, v[4:7]
	s_mov_b64 exec, s[98:99]
	s_waitcnt vmcnt(3) lgkmcnt(0)
	s_barrier
	ds_read_b32 v0, v3
	v_lshlrev_b32_e32 v1, 10, v232
	v_lshlrev_b32_e32 v2, 4, v254
	v_add3_u32 v241, 0, v1, v2
	s_cmp_lg_u32 s52, 0
	s_waitcnt lgkmcnt(0)
	v_add_f32_e32 v0, 0x41800000, v0
	v_xor_b32_e32 v32, 0x80000000, v0
	v_mov_b32_e32 v33, v32
	v_mov_b32_e32 v34, v32
	v_mov_b32_e32 v35, v32
	v_mov_b32_e32 v36, v32
	v_mov_b32_e32 v37, v32
	v_mov_b32_e32 v38, v32
	v_mov_b32_e32 v39, v32
	v_mov_b32_e32 v40, v32
	v_mov_b32_e32 v41, v32
	v_mov_b32_e32 v42, v32
	v_mov_b32_e32 v43, v32
	v_mov_b32_e32 v44, v32
	v_mov_b32_e32 v45, v32
	v_mov_b32_e32 v46, v32
	v_mov_b32_e32 v47, v32
	ds_read_b128 v[0:3], v241
	ds_read_b128 v[50:53], v241 offset:512
	s_cselect_b64 s[4:5], -1, 0
	v_lshlrev_b32_e32 v222, 2, v232
	s_and_b64 vcc, exec, s[4:5]
	s_waitcnt vmcnt(3) lgkmcnt(1)
	v_mfma_f32_32x32x16_bf16 v[16:31], v[0:3], v[140:143], v[32:47]
	s_waitcnt lgkmcnt(0)
	v_mfma_f32_32x32x16_bf16 v[0:15], v[50:53], v[140:143], v[32:47]
	ds_read_b128 v[50:53], v241 offset:2048
	s_waitcnt vmcnt(2) lgkmcnt(0)
	v_mfma_f32_32x32x16_bf16 v[16:31], v[50:53], v[136:139], v[16:31]
	ds_read_b128 v[50:53], v241 offset:2560
	s_waitcnt lgkmcnt(0)
	v_mfma_f32_32x32x16_bf16 v[0:15], v[50:53], v[136:139], v[0:15]
	ds_read_b128 v[50:53], v241 offset:4096
	s_waitcnt vmcnt(1) lgkmcnt(0)
	v_mfma_f32_32x32x16_bf16 v[16:31], v[50:53], v[132:135], v[16:31]
	ds_read_b128 v[50:53], v241 offset:4608
	s_waitcnt lgkmcnt(0)
	v_mfma_f32_32x32x16_bf16 v[0:15], v[50:53], v[132:135], v[0:15]
	ds_read_b128 v[50:53], v241 offset:6144
	s_waitcnt vmcnt(0) lgkmcnt(0)
	v_mfma_f32_32x32x16_bf16 v[16:31], v[50:53], v[128:131], v[16:31]
	ds_read_b128 v[50:53], v241 offset:6656
	s_waitcnt lgkmcnt(0)
	v_mfma_f32_32x32x16_bf16 v[0:15], v[50:53], v[128:131], v[0:15]
	s_nop 15
	s_nop 7
	s_cbranch_vccnz .LBB0_510
	v_or_b32_e32 v50, 32, v222
	v_cmp_le_i32_e32 vcc, v50, v239
	v_or_b32_e32 v50, 33, v222
	s_nop 7
	v_cndmask_b32_e32 v0, v233, v0, vcc
	v_cmp_lt_i32_e32 vcc, v222, v239
	s_nop 1
	v_cndmask_b32_e32 v17, v233, v17, vcc
	v_cmp_le_i32_e32 vcc, v222, v239
	s_nop 1
	v_cndmask_b32_e32 v16, v233, v16, vcc
	v_cmp_le_i32_e32 vcc, v50, v239
	v_or_b32_e32 v50, 2, v222
	s_nop 0
	v_cndmask_b32_e32 v1, v233, v1, vcc
	v_cmp_le_i32_e32 vcc, v50, v239
	v_or_b32_e32 v50, 34, v222
	s_nop 0
	v_cndmask_b32_e32 v18, v233, v18, vcc
	v_cmp_le_i32_e32 vcc, v50, v239
	v_or_b32_e32 v50, 3, v222
	s_nop 0
	v_cndmask_b32_e32 v2, v233, v2, vcc
	v_cmp_le_i32_e32 vcc, v50, v239
	v_or_b32_e32 v50, 35, v222
	s_nop 0
	v_cndmask_b32_e32 v19, v233, v19, vcc
	v_cmp_le_i32_e32 vcc, v50, v239
	v_or_b32_e32 v50, 8, v222
	s_nop 0
	v_cndmask_b32_e32 v3, v233, v3, vcc
	v_cmp_le_i32_e32 vcc, v50, v239
	v_or_b32_e32 v50, 40, v222
	s_nop 0
	v_cndmask_b32_e32 v20, v233, v20, vcc
	v_cmp_le_i32_e32 vcc, v50, v239
	v_or_b32_e32 v50, 9, v222
	s_nop 0
	v_cndmask_b32_e32 v4, v233, v4, vcc
	v_cmp_le_i32_e32 vcc, v50, v239
	v_or_b32_e32 v50, 41, v222
	s_nop 0
	v_cndmask_b32_e32 v21, v233, v21, vcc
	v_cmp_le_i32_e32 vcc, v50, v239
	v_or_b32_e32 v50, 10, v222
	s_nop 0
	v_cndmask_b32_e32 v5, v233, v5, vcc
	v_cmp_le_i32_e32 vcc, v50, v239
	v_or_b32_e32 v50, 42, v222
	s_nop 0
	v_cndmask_b32_e32 v22, v233, v22, vcc
	v_cmp_le_i32_e32 vcc, v50, v239
	v_or_b32_e32 v50, 11, v222
	s_nop 0
	v_cndmask_b32_e32 v6, v233, v6, vcc
	v_cmp_le_i32_e32 vcc, v50, v239
	v_or_b32_e32 v50, 43, v222
	s_nop 0
	v_cndmask_b32_e32 v23, v233, v23, vcc
	v_cmp_le_i32_e32 vcc, v50, v239
	v_or_b32_e32 v50, 16, v222
	s_nop 0
	v_cndmask_b32_e32 v7, v233, v7, vcc
	v_cmp_le_i32_e32 vcc, v50, v239
	v_or_b32_e32 v50, 48, v222
	s_nop 0
	v_cndmask_b32_e32 v24, v233, v24, vcc
	v_cmp_le_i32_e32 vcc, v50, v239
	v_or_b32_e32 v50, 17, v222
	s_nop 0
	v_cndmask_b32_e32 v8, v233, v8, vcc
	v_cmp_le_i32_e32 vcc, v50, v239
	v_or_b32_e32 v50, 49, v222
	s_nop 0
	v_cndmask_b32_e32 v25, v233, v25, vcc
	v_cmp_le_i32_e32 vcc, v50, v239
	v_or_b32_e32 v50, 18, v222
	s_nop 0
	v_cndmask_b32_e32 v9, v233, v9, vcc
	v_cmp_le_i32_e32 vcc, v50, v239
	v_or_b32_e32 v50, 50, v222
	s_nop 0
	v_cndmask_b32_e32 v26, v233, v26, vcc
	v_cmp_le_i32_e32 vcc, v50, v239
	v_or_b32_e32 v50, 19, v222
	s_nop 0
	v_cndmask_b32_e32 v10, v233, v10, vcc
	v_cmp_le_i32_e32 vcc, v50, v239
	v_or_b32_e32 v50, 51, v222
	s_nop 0
	v_cndmask_b32_e32 v27, v233, v27, vcc
	v_cmp_le_i32_e32 vcc, v50, v239
	v_or_b32_e32 v50, 24, v222
	s_nop 0
	v_cndmask_b32_e32 v11, v233, v11, vcc
	v_cmp_le_i32_e32 vcc, v50, v239
	v_or_b32_e32 v50, 56, v222
	s_nop 0
	v_cndmask_b32_e32 v28, v233, v28, vcc
	v_cmp_le_i32_e32 vcc, v50, v239
	v_or_b32_e32 v50, 25, v222
	s_nop 0
	v_cndmask_b32_e32 v12, v233, v12, vcc
	v_cmp_le_i32_e32 vcc, v50, v239
	v_or_b32_e32 v50, 57, v222
	s_nop 0
	v_cndmask_b32_e32 v29, v233, v29, vcc
	v_cmp_le_i32_e32 vcc, v50, v239
	v_or_b32_e32 v50, 26, v222
	s_nop 0
	v_cndmask_b32_e32 v13, v233, v13, vcc
	v_cmp_le_i32_e32 vcc, v50, v239
	v_or_b32_e32 v50, 58, v222
	s_nop 0
	v_cndmask_b32_e32 v30, v233, v30, vcc
	v_cmp_le_i32_e32 vcc, v50, v239
	v_or_b32_e32 v50, 27, v222
	s_nop 0
	v_cndmask_b32_e32 v14, v233, v14, vcc
	v_cmp_le_i32_e32 vcc, v50, v239
	v_or_b32_e32 v50, 59, v222
	s_nop 0
	v_cndmask_b32_e32 v31, v233, v31, vcc
	v_cmp_le_i32_e32 vcc, v50, v239
	s_nop 1
	v_cndmask_b32_e32 v15, v233, v15, vcc

.LBB0_876:
	s_mov_b32 s98, 0
	s_cmp_eq_u32 s8, 1
	s_cselect_b32 s98, 0x5600, s98
	s_cmp_eq_u32 s8, 2
	s_cselect_b32 s98, 0xac00, s98
	s_cmp_eq_u32 s8, 4
	s_cselect_b32 s98, 0x2b00, s98
	s_cmp_eq_u32 s8, 5
	s_cselect_b32 s98, 0x8100, s98
	s_cmp_eq_u32 s8, 6
	s_cselect_b32 s98, 0xd700, s98
	s_cmp_eq_u32 s8, 7
	s_cselect_b32 s98, 0x2b00, s98
	s_and_b32 s99, s8, 3
	s_cmp_eq_u32 s99, 3
	s_cselect_b32 s100, s48, s46
	s_cselect_b32 s101, s49, s47
	s_add_u32 s98, s100, s98
	s_addc_u32 s99, s101, 0
	v_mbcnt_lo_u32_b32 v254, -1, 0
	v_mbcnt_hi_u32_b32 v254, -1, v254
	s_lshl_b32 s100, s8, 9
	v_lshlrev_b32_e32 v254, 3, v254
	s_add_i32 s100, s100, 0x22c00
	v_add_u32_e32 v241, s100, v254
	s_mov_b32 s100, 0xbfb8aa3b
	s_bitcmp1_b32 s8, 2
	s_cselect_b32 s100, 0xbf317218, s100
	s_lshl_b32 s8, s8, 5
	s_and_b32 s26, s8, 0x60
	s_lshl_b32 s22, s7, 13
	s_lshl_b32 s23, s26, 7
	s_add_u32 s8, s30, 0x4b0000
	s_mov_b64 s[10:11], 0x80
	s_addc_u32 s9, s31, 0
	s_add_i32 m0, s71, 0x18000
	v_lshl_add_u64 v[6:7], v[6:7], 0, s[10:11]
	s_waitcnt vmcnt(2)
	s_barrier
	global_load_lds_dwordx4 v[6:7], off
	v_lshl_add_u64 v[4:5], v[4:5], 0, s[10:11]
	s_add_i32 m0, s71, 0x1a000
	s_add_i32 s78, s71, 0x8000
	s_add_i32 s79, s71, 0xa000
	global_load_lds_dwordx4 v[4:5], off
	v_lshl_add_u64 v[2:3], v[2:3], 0, s[10:11]
	s_mov_b32 m0, s78
	s_add_u32 s18, s64, 0x40080
	global_load_lds_dwordx4 v[2:3], off
	v_lshl_add_u64 v[0:1], v[0:1], 0, s[10:11]
	s_mov_b32 m0, s79
	s_addc_u32 s19, s65, 0
	global_load_lds_dwordx4 v[0:1], off
	s_add_i32 m0, s71, 0x1c000
	v_lshl_add_u64 v[0:1], s[18:19], 0, v[138:139]
	global_load_lds_dwordx4 v[0:1], off
	v_lshl_add_u64 v[0:1], s[18:19], 0, v[142:143]
	s_add_i32 m0, s71, 0x1e000
	v_and_b32_e32 v234, 15, v8
	global_load_lds_dwordx4 v[0:1], off
	v_lshrrev_b32_e32 v0, 1, v8
	s_cmpk_lt_u32 s6, 0x100
	v_and_b32_e32 v0, 24, v0
	v_lshlrev_b32_e32 v1, 6, v234
	v_lshlrev_b32_e32 v2, 2, v8
	s_cselect_b64 s[18:19], -1, 0
	s_lshl_b32 s81, s7, 2
	v_lshl_or_b32 v1, v0, 1, v1
	v_and_b32_e32 v2, 32, v2
	s_ashr_i32 s82, s81, 31
	v_bitop3_b32 v3, v1, s22, v2 bitop3:0xde
	s_add_u32 s22, s46, 0x5600
	v_bitop3_b32 v235, v1, s23, v2 bitop3:0xde
	s_addc_u32 s23, s47, 0
	s_add_u32 s24, s46, 0xac00
	v_lshlrev_b32_e32 v1, 3, v234
	s_addc_u32 s25, s47, 0
	v_lshl_or_b32 v236, s7, 7, v1
	s_add_u32 s36, s46, 0x2b00
	v_and_b32_e32 v1, 1, v9
	s_addc_u32 s37, s47, 0
	v_or_b32_e32 v237, s26, v0
	v_add3_u32 v0, v11, v12, v13
	v_lshlrev_b32_e32 v1, 6, v1
	s_add_u32 s38, s46, 0x8100
	v_lshl_or_b32 v0, v0, 11, v1
	s_addc_u32 s39, s47, 0
	v_lshl_add_u32 v0, v10, 1, v0
	v_mov_b32_e32 v1, v139
	s_mov_b64 s[6:7], 0x2080
	s_add_u32 s40, s46, 0xd700
	v_lshl_add_u64 v[144:145], v[0:1], 0, s[6:7]
	v_and_b32_e32 v1, 1, v14
	s_addc_u32 s41, s47, 0
	v_add3_u32 v0, v16, v17, v18
	v_lshlrev_b32_e32 v1, 6, v1
	s_waitcnt vmcnt(6)
	s_add_u32 s42, s48, 0x2b00
	v_lshl_or_b32 v0, v0, 11, v1
	s_addc_u32 s43, s49, 0
	v_lshl_add_u32 v0, v15, 1, v0
	v_mov_b32_e32 v1, v139
	s_add_i32 s88, 0, 0x10000
	s_add_i32 s89, 0, 0x14000
	s_mov_b32 s80, 0x8000
	v_lshl_add_u64 v[146:147], v[0:1], 0, s[6:7]
	v_mov_b64_e32 v[148:149], 0xb00
	v_mov_b64_e32 v[150:151], 0xaff
	s_movk_i32 s83, 0x161
	v_add_u32_e32 v238, s88, v235
	v_add_u32_e32 v239, s89, v235
	v_add_u32_e32 v240, 0, v3
	s_mov_b64 s[44:45], 0x5800
	s_movk_i32 s90, 0x5000
	s_movk_i32 s91, 0x1000
	s_movk_i32 s92, 0xac0
	s_movk_i32 s93, 0x1600
	s_barrier
	s_branch .LBB0_879

.LBB0_879:
	v_lshrrev_b32_e32 v244, 2, v254
	v_lshl_add_u32 v244, s60, 7, v244
	v_mov_b32_e32 v226, 0
	v_mov_b32_e32 v227, 0
	v_lshl_add_u32 v245, s60, 9, v254
	v_cmp_gt_u32_e32 vcc, 0xac0, v244
	v_lshl_add_u32 v246, s58, 8, v236
	v_lshlrev_b32_e32 v246, 2, v246
	s_and_saveexec_b64 vcc, vcc
	global_load_dwordx2 v[226:227], v245, s[98:99]
	s_mov_b64 exec, vcc
	global_load_dwordx4 v[218:221], v246, s[8:9]
	global_load_dwordx4 v[222:225], v246, s[8:9] offset:16
	s_add_i32 s76, s76, 1
	s_mul_i32 s6, s76, s21
	s_mul_hi_u32 s7, s76, s20
	s_add_i32 s7, s7, s6
	s_mul_i32 s6, s76, s20
	s_add_u32 s54, s6, s2
	s_addc_u32 s55, s7, s3
	v_cmp_gt_i64_e32 vcc, s[54:55], v[150:151]
	v_cmp_lt_i64_e64 s[6:7], s[54:55], v[148:149]
	s_cbranch_vccnz .LBB0_881
	s_ashr_i32 s26, s54, 31
	s_lshr_b32 s26, s26, 29
	s_add_i32 s26, s54, s26
	s_ashr_i32 s27, s26, 3
	s_and_b32 s26, s26, -8
	s_sub_i32 s26, s54, s26
	s_cmp_lt_i32 s26, 0
	s_cselect_b32 s50, s83, 0x160
	s_mul_i32 s26, s26, s50
	s_add_i32 s26, s26, s27
	s_mul_hi_i32 s27, s26, 0x3e0f83e1
	s_lshr_b32 s50, s27, 31
	s_ashr_i32 s27, s27, 5
	s_add_i32 s27, s27, s50
	s_mul_i32 s51, s27, 6
	s_sub_i32 s50, 0x80, s51
	s_min_i32 s52, s50, 6
	s_abs_i32 s50, s52
	v_cvt_f32_u32_e32 v0, s50
	s_sub_i32 s54, 0, s50
	s_mulk_i32 s27, 0x84
	s_sub_i32 s26, s26, s27
	v_rcp_iflag_f32_e32 v0, v0
	s_abs_i32 s27, s26
	s_xor_b32 s53, s26, s52
	s_ashr_i32 s53, s53, 31
	v_mul_f32_e32 v0, 0x4f7ffffe, v0
	v_cvt_u32_f32_e32 v0, v0
	s_nop 0
	v_readfirstlane_b32 s55, v0
	s_mul_i32 s54, s54, s55
	s_mul_hi_u32 s54, s55, s54
	s_add_i32 s55, s55, s54
	s_mul_hi_u32 s54, s27, s55
	s_mul_i32 s55, s54, s50
	s_sub_i32 s27, s27, s55
	s_add_i32 s56, s54, 1
	s_sub_i32 s55, s27, s50
	s_cmp_ge_u32 s27, s50
	s_cselect_b32 s54, s56, s54
	s_cselect_b32 s27, s55, s27
	s_add_i32 s55, s54, 1
	s_cmp_ge_u32 s27, s50
	s_cselect_b32 s27, s55, s54
	s_xor_b32 s27, s27, s53
	s_sub_i32 s50, s27, s53
	s_mul_i32 s27, s50, s52
	s_sub_i32 s26, s26, s27
	s_add_i32 s52, s51, s26

.LBB0_882:
	ds_read_b128 v[64:67], v238
	ds_read_b128 v[68:71], v238 offset:1024
	ds_read_b128 v[152:155], v238 offset:2048
	ds_read_b128 v[156:159], v238 offset:3072
	ds_read_b128 v[160:163], v239
	ds_read_b128 v[164:167], v239 offset:1024
	ds_read_b128 v[168:171], v239 offset:2048
	ds_read_b128 v[172:175], v239 offset:3072
	s_add_u32 s64, s62, 0x100
	s_addc_u32 s65, s63, 0
	s_cmp_eq_u32 s96, 12
	s_cselect_b32 s69, s53, s65
	s_cselect_b32 s68, s59, s64
	s_cselect_b32 s67, s51, s95
	s_cselect_b32 s66, s61, s94
	v_lshl_add_u64 v[208:209], s[62:63], 0, v[144:145]
	s_add_i32 m0, s71, 0xc000
	ds_read_b128 v[176:179], v240
	ds_read_b128 v[180:183], v240 offset:1024
	ds_read_b128 v[184:187], v240 offset:2048
	ds_read_b128 v[188:191], v240 offset:3072
	ds_read_b128 v[192:195], v240 offset:4096
	ds_read_b128 v[196:199], v240 offset:5120
	ds_read_b128 v[200:203], v240 offset:6144
	ds_read_b128 v[204:207], v240 offset:7168
	global_load_lds_dwordx4 v[208:209], off
	v_lshl_add_u64 v[208:209], s[62:63], 0, v[146:147]
	s_add_i32 m0, s71, 0xe000
	s_nop 0
	global_load_lds_dwordx4 v[208:209], off
	s_waitcnt vmcnt(8)
	s_waitcnt lgkmcnt(0)
	s_barrier
	s_setprio 1
	s_waitcnt lgkmcnt(0)
	v_mfma_f32_16x16x32_bf16 v[104:107], v[64:67], v[176:179], v[104:107]
	v_mfma_f32_16x16x32_bf16 v[96:99], v[152:155], v[176:179], v[96:99]
	v_mfma_f32_16x16x32_bf16 v[92:95], v[64:67], v[184:187], v[92:95]
	v_mfma_f32_16x16x32_bf16 v[88:91], v[152:155], v[184:187], v[88:91]
	v_mfma_f32_16x16x32_bf16 v[60:63], v[64:67], v[192:195], v[60:63]
	v_mfma_f32_16x16x32_bf16 v[28:31], v[152:155], v[192:195], v[28:31]
	v_mfma_f32_16x16x32_bf16 v[56:59], v[64:67], v[200:203], v[56:59]
	v_mfma_f32_16x16x32_bf16 v[24:27], v[152:155], v[200:203], v[24:27]
	v_mfma_f32_16x16x32_bf16 v[104:107], v[68:71], v[180:183], v[104:107]
	v_mfma_f32_16x16x32_bf16 v[96:99], v[156:159], v[180:183], v[96:99]
	v_mfma_f32_16x16x32_bf16 v[92:95], v[68:71], v[188:191], v[92:95]
	v_mfma_f32_16x16x32_bf16 v[88:91], v[156:159], v[188:191], v[88:91]
	v_mfma_f32_16x16x32_bf16 v[60:63], v[68:71], v[196:199], v[60:63]
	v_mfma_f32_16x16x32_bf16 v[28:31], v[156:159], v[196:199], v[28:31]
	v_mfma_f32_16x16x32_bf16 v[56:59], v[68:71], v[204:207], v[56:59]
	v_mfma_f32_16x16x32_bf16 v[24:27], v[156:159], v[204:207], v[24:27]
	s_setprio 0
	s_setprio 1
	v_mfma_f32_16x16x32_bf16 v[84:87], v[160:163], v[176:179], v[84:87]
	v_mfma_f32_16x16x32_bf16 v[80:83], v[168:171], v[176:179], v[80:83]
	v_mfma_f32_16x16x32_bf16 v[76:79], v[160:163], v[184:187], v[76:79]
	v_mfma_f32_16x16x32_bf16 v[72:75], v[168:171], v[184:187], v[72:75]
	v_mfma_f32_16x16x32_bf16 v[48:51], v[160:163], v[192:195], v[48:51]
	v_mfma_f32_16x16x32_bf16 v[16:19], v[168:171], v[192:195], v[16:19]
	v_mfma_f32_16x16x32_bf16 v[40:43], v[160:163], v[200:203], v[40:43]
	v_mfma_f32_16x16x32_bf16 v[8:11], v[168:171], v[200:203], v[8:11]
	v_mfma_f32_16x16x32_bf16 v[84:87], v[164:167], v[180:183], v[84:87]
	v_mfma_f32_16x16x32_bf16 v[80:83], v[172:175], v[180:183], v[80:83]
	v_mfma_f32_16x16x32_bf16 v[76:79], v[164:167], v[188:191], v[76:79]
	v_mfma_f32_16x16x32_bf16 v[72:75], v[172:175], v[188:191], v[72:75]
	v_mfma_f32_16x16x32_bf16 v[48:51], v[164:167], v[196:199], v[48:51]
	v_mfma_f32_16x16x32_bf16 v[16:19], v[172:175], v[196:199], v[16:19]
	v_mfma_f32_16x16x32_bf16 v[40:43], v[164:167], v[204:207], v[40:43]
	v_mfma_f32_16x16x32_bf16 v[8:11], v[172:175], v[204:207], v[8:11]
	s_setprio 0
	s_barrier
	s_add_i32 s26, s88, s70
	v_lshl_add_u64 v[208:209], s[66:67], 0, v[138:139]
	s_mov_b32 m0, s26
	ds_read_b128 v[176:179], v240 offset:16384
	ds_read_b128 v[180:183], v240 offset:17408
	ds_read_b128 v[184:187], v240 offset:18432
	ds_read_b128 v[188:191], v240 offset:19456
	ds_read_b128 v[192:195], v240 offset:20480
	ds_read_b128 v[196:199], v240 offset:21504
	ds_read_b128 v[200:203], v240 offset:22528
	ds_read_b128 v[204:207], v240 offset:23552
	global_load_lds_dwordx4 v[208:209], off
	s_add_i32 m0, s26, 0x2000
	s_add_u32 s26, s66, 0x40000
	v_lshl_add_u64 v[210:211], s[66:67], 0, v[142:143]
	s_addc_u32 s27, s67, 0
	s_add_i32 s62, s89, s70
	global_load_lds_dwordx4 v[210:211], off
	v_lshl_add_u64 v[212:213], s[26:27], 0, v[138:139]
	s_mov_b32 m0, s62
	v_lshl_add_u64 v[214:215], s[68:69], 0, v[140:141]
	global_load_lds_dwordx4 v[212:213], off
	v_lshl_add_u64 v[212:213], s[26:27], 0, v[142:143]
	s_add_i32 m0, s62, 0x2000
	s_nop 0
	global_load_lds_dwordx4 v[212:213], off
	v_lshl_add_u64 v[212:213], s[68:69], 0, v[136:137]
	s_mov_b32 m0, s71
	s_nop 0
	global_load_lds_dwordx4 v[212:213], off
	s_mov_b32 m0, s72
	s_nop 0
	global_load_lds_dwordx4 v[214:215], off
	s_waitcnt vmcnt(8)
	v_mul_f32_e32 v248, s100, v226
	v_mul_f32_e32 v249, s100, v227
	ds_write_b64 v241, v[248:249]
	s_waitcnt lgkmcnt(0)
	s_barrier
	s_setprio 1
	s_waitcnt lgkmcnt(0)
	v_mfma_f32_16x16x32_bf16 v[52:55], v[64:67], v[176:179], v[52:55]
	v_mfma_f32_16x16x32_bf16 v[20:23], v[152:155], v[176:179], v[20:23]
	v_mfma_f32_16x16x32_bf16 v[44:47], v[64:67], v[184:187], v[44:47]
	v_mfma_f32_16x16x32_bf16 v[12:15], v[152:155], v[184:187], v[12:15]
	v_mfma_f32_16x16x32_bf16 v[132:135], v[64:67], v[192:195], v[132:135]
	v_mfma_f32_16x16x32_bf16 v[128:131], v[152:155], v[192:195], v[128:131]
	v_mfma_f32_16x16x32_bf16 v[64:67], v[64:67], v[200:203], v[124:127]
	v_mfma_f32_16x16x32_bf16 v[52:55], v[68:71], v[180:183], v[52:55]
	v_mfma_f32_16x16x32_bf16 v[20:23], v[156:159], v[180:183], v[20:23]
	v_mfma_f32_16x16x32_bf16 v[44:47], v[68:71], v[188:191], v[44:47]
	v_mfma_f32_16x16x32_bf16 v[12:15], v[156:159], v[188:191], v[12:15]
	v_mfma_f32_16x16x32_bf16 v[132:135], v[68:71], v[196:199], v[132:135]
	v_mfma_f32_16x16x32_bf16 v[128:131], v[156:159], v[196:199], v[128:131]
	v_mfma_f32_16x16x32_bf16 v[64:67], v[68:71], v[204:207], v[64:67]
	v_mfma_f32_16x16x32_bf16 v[68:71], v[152:155], v[200:203], v[120:123]
	v_mfma_f32_16x16x32_bf16 v[68:71], v[156:159], v[204:207], v[68:71]
	s_setprio 0
	s_setprio 1
	v_mfma_f32_16x16x32_bf16 v[36:39], v[160:163], v[176:179], v[36:39]
	v_mfma_f32_16x16x32_bf16 v[4:7], v[168:171], v[176:179], v[4:7]
	v_mfma_f32_16x16x32_bf16 v[32:35], v[160:163], v[184:187], v[32:35]
	v_mfma_f32_16x16x32_bf16 v[0:3], v[168:171], v[184:187], v[0:3]
	v_mfma_f32_16x16x32_bf16 v[116:119], v[160:163], v[192:195], v[116:119]
	v_mfma_f32_16x16x32_bf16 v[112:115], v[168:171], v[192:195], v[112:115]
	v_mfma_f32_16x16x32_bf16 v[108:111], v[160:163], v[200:203], v[108:111]
	v_mfma_f32_16x16x32_bf16 v[100:103], v[168:171], v[200:203], v[100:103]
	v_mfma_f32_16x16x32_bf16 v[36:39], v[164:167], v[180:183], v[36:39]
	v_mfma_f32_16x16x32_bf16 v[4:7], v[172:175], v[180:183], v[4:7]
	v_mfma_f32_16x16x32_bf16 v[32:35], v[164:167], v[188:191], v[32:35]
	v_mfma_f32_16x16x32_bf16 v[0:3], v[172:175], v[188:191], v[0:3]
	v_mfma_f32_16x16x32_bf16 v[116:119], v[164:167], v[196:199], v[116:119]
	v_mfma_f32_16x16x32_bf16 v[112:115], v[172:175], v[196:199], v[112:115]
	v_mfma_f32_16x16x32_bf16 v[108:111], v[164:167], v[204:207], v[108:111]
	v_mfma_f32_16x16x32_bf16 v[100:103], v[172:175], v[204:207], v[100:103]
	s_setprio 0
	s_barrier
	s_add_i32 s62, 0, 0x18000
	s_add_i32 s63, 0, 0x1c000
	v_add_u32_e32 v156, s62, v235
	v_add_u32_e32 v172, s63, v235
	ds_read_b128 v[120:123], v156
	ds_read_b128 v[124:127], v156 offset:1024
	ds_read_b128 v[152:155], v156 offset:2048
	ds_read_b128 v[156:159], v156 offset:3072
	ds_read_b128 v[160:163], v172
	ds_read_b128 v[164:167], v172 offset:1024
	ds_read_b128 v[168:171], v172 offset:2048
	ds_read_b128 v[172:175], v172 offset:3072
	s_add_u32 s26, s68, 0x2000
	s_addc_u32 s27, s69, 0
	s_mov_b32 m0, s73
	v_lshl_add_u64 v[216:217], s[26:27], 0, v[136:137]
	ds_read_b128 v[176:179], v240 offset:32768
	ds_read_b128 v[180:183], v240 offset:33792
	ds_read_b128 v[184:187], v240 offset:34816
	ds_read_b128 v[188:191], v240 offset:35840
	ds_read_b128 v[192:195], v240 offset:36864
	ds_read_b128 v[196:199], v240 offset:37888
	ds_read_b128 v[200:203], v240 offset:38912
	ds_read_b128 v[204:207], v240 offset:39936
	global_load_lds_dwordx4 v[216:217], off
	v_lshl_add_u64 v[216:217], s[26:27], 0, v[140:141]
	s_mov_b32 m0, s74
	s_nop 0
	global_load_lds_dwordx4 v[216:217], off
	s_waitcnt vmcnt(8)
	s_waitcnt lgkmcnt(0)
	s_barrier
	s_setprio 1
	s_waitcnt lgkmcnt(0)
	v_mfma_f32_16x16x32_bf16 v[104:107], v[120:123], v[176:179], v[104:107]
	v_mfma_f32_16x16x32_bf16 v[96:99], v[152:155], v[176:179], v[96:99]
	v_mfma_f32_16x16x32_bf16 v[92:95], v[120:123], v[184:187], v[92:95]
	v_mfma_f32_16x16x32_bf16 v[88:91], v[152:155], v[184:187], v[88:91]
	v_mfma_f32_16x16x32_bf16 v[60:63], v[120:123], v[192:195], v[60:63]
	v_mfma_f32_16x16x32_bf16 v[28:31], v[152:155], v[192:195], v[28:31]
	v_mfma_f32_16x16x32_bf16 v[56:59], v[120:123], v[200:203], v[56:59]
	v_mfma_f32_16x16x32_bf16 v[24:27], v[152:155], v[200:203], v[24:27]
	v_mfma_f32_16x16x32_bf16 v[104:107], v[124:127], v[180:183], v[104:107]
	v_mfma_f32_16x16x32_bf16 v[96:99], v[156:159], v[180:183], v[96:99]
	v_mfma_f32_16x16x32_bf16 v[92:95], v[124:127], v[188:191], v[92:95]
	v_mfma_f32_16x16x32_bf16 v[88:91], v[156:159], v[188:191], v[88:91]
	v_mfma_f32_16x16x32_bf16 v[60:63], v[124:127], v[196:199], v[60:63]
	v_mfma_f32_16x16x32_bf16 v[28:31], v[156:159], v[196:199], v[28:31]
	v_mfma_f32_16x16x32_bf16 v[56:59], v[124:127], v[204:207], v[56:59]
	v_mfma_f32_16x16x32_bf16 v[24:27], v[156:159], v[204:207], v[24:27]
	s_setprio 0
	s_setprio 1
	v_mfma_f32_16x16x32_bf16 v[84:87], v[160:163], v[176:179], v[84:87]
	v_mfma_f32_16x16x32_bf16 v[80:83], v[168:171], v[176:179], v[80:83]
	v_mfma_f32_16x16x32_bf16 v[76:79], v[160:163], v[184:187], v[76:79]
	v_mfma_f32_16x16x32_bf16 v[72:75], v[168:171], v[184:187], v[72:75]
	v_mfma_f32_16x16x32_bf16 v[48:51], v[160:163], v[192:195], v[48:51]
	v_mfma_f32_16x16x32_bf16 v[16:19], v[168:171], v[192:195], v[16:19]
	v_mfma_f32_16x16x32_bf16 v[40:43], v[160:163], v[200:203], v[40:43]
	v_mfma_f32_16x16x32_bf16 v[8:11], v[168:171], v[200:203], v[8:11]
	v_mfma_f32_16x16x32_bf16 v[84:87], v[164:167], v[180:183], v[84:87]
	v_mfma_f32_16x16x32_bf16 v[80:83], v[172:175], v[180:183], v[80:83]
	v_mfma_f32_16x16x32_bf16 v[76:79], v[164:167], v[188:191], v[76:79]
	v_mfma_f32_16x16x32_bf16 v[72:75], v[172:175], v[188:191], v[72:75]
	v_mfma_f32_16x16x32_bf16 v[48:51], v[164:167], v[196:199], v[48:51]
	v_mfma_f32_16x16x32_bf16 v[16:19], v[172:175], v[196:199], v[16:19]
	v_mfma_f32_16x16x32_bf16 v[40:43], v[164:167], v[204:207], v[40:43]
	v_mfma_f32_16x16x32_bf16 v[8:11], v[172:175], v[204:207], v[8:11]
	s_setprio 0
	s_barrier
	s_add_i32 s26, s62, s70
	v_lshl_add_u64 v[208:209], v[208:209], 0, s[10:11]
	s_mov_b32 m0, s26
	ds_read_b128 v[176:179], v240 offset:49152
	ds_read_b128 v[180:183], v240 offset:50176
	ds_read_b128 v[184:187], v240 offset:51200
	ds_read_b128 v[188:191], v240 offset:52224
	ds_read_b128 v[192:195], v240 offset:53248
	ds_read_b128 v[196:199], v240 offset:54272
	ds_read_b128 v[200:203], v240 offset:55296
	ds_read_b128 v[204:207], v240 offset:56320
	global_load_lds_dwordx4 v[208:209], off
	s_add_i32 m0, s26, 0x2000
	s_add_u32 s26, s66, 0x40080
	v_lshl_add_u64 v[208:209], v[210:211], 0, s[10:11]
	s_addc_u32 s27, s67, 0
	s_add_i32 s62, s63, s70
	global_load_lds_dwordx4 v[208:209], off
	v_lshl_add_u64 v[208:209], s[26:27], 0, v[138:139]
	s_mov_b32 m0, s62
	s_nop 0
	global_load_lds_dwordx4 v[208:209], off
	v_lshl_add_u64 v[208:209], s[26:27], 0, v[142:143]
	s_add_i32 m0, s62, 0x2000
	s_nop 0
	global_load_lds_dwordx4 v[208:209], off
	v_lshl_add_u64 v[208:209], v[212:213], 0, s[10:11]
	s_mov_b32 m0, s78
	s_nop 0
	global_load_lds_dwordx4 v[208:209], off
	v_lshl_add_u64 v[208:209], v[214:215], 0, s[10:11]
	s_mov_b32 m0, s79
	s_nop 0
	global_load_lds_dwordx4 v[208:209], off
	s_waitcnt vmcnt(8)
	s_waitcnt lgkmcnt(0)
	s_barrier
	s_setprio 1
	s_waitcnt lgkmcnt(0)
	v_mfma_f32_16x16x32_bf16 v[52:55], v[120:123], v[176:179], v[52:55]
	v_mfma_f32_16x16x32_bf16 v[44:47], v[120:123], v[184:187], v[44:47]
	v_mfma_f32_16x16x32_bf16 v[132:135], v[120:123], v[192:195], v[132:135]
	v_mfma_f32_16x16x32_bf16 v[64:67], v[120:123], v[200:203], v[64:67]
	v_mfma_f32_16x16x32_bf16 v[52:55], v[124:127], v[180:183], v[52:55]
	v_mfma_f32_16x16x32_bf16 v[20:23], v[152:155], v[176:179], v[20:23]
	v_mfma_f32_16x16x32_bf16 v[44:47], v[124:127], v[188:191], v[44:47]
	v_mfma_f32_16x16x32_bf16 v[12:15], v[152:155], v[184:187], v[12:15]
	v_mfma_f32_16x16x32_bf16 v[132:135], v[124:127], v[196:199], v[132:135]
	v_mfma_f32_16x16x32_bf16 v[128:131], v[152:155], v[192:195], v[128:131]
	v_mfma_f32_16x16x32_bf16 v[124:127], v[124:127], v[204:207], v[64:67]
	v_mfma_f32_16x16x32_bf16 v[64:67], v[152:155], v[200:203], v[68:71]
	v_mfma_f32_16x16x32_bf16 v[20:23], v[156:159], v[180:183], v[20:23]
	v_mfma_f32_16x16x32_bf16 v[12:15], v[156:159], v[188:191], v[12:15]
	v_mfma_f32_16x16x32_bf16 v[128:131], v[156:159], v[196:199], v[128:131]
	v_mfma_f32_16x16x32_bf16 v[120:123], v[156:159], v[204:207], v[64:67]
	s_setprio 0
	s_setprio 1
	v_mfma_f32_16x16x32_bf16 v[64:67], v[160:163], v[192:195], v[116:119]
	v_mfma_f32_16x16x32_bf16 v[116:119], v[164:167], v[196:199], v[64:67]
	v_mfma_f32_16x16x32_bf16 v[64:67], v[168:171], v[192:195], v[112:115]
	v_mfma_f32_16x16x32_bf16 v[112:115], v[172:175], v[196:199], v[64:67]
	v_mfma_f32_16x16x32_bf16 v[64:67], v[160:163], v[200:203], v[108:111]
	v_mfma_f32_16x16x32_bf16 v[36:39], v[160:163], v[176:179], v[36:39]
	v_mfma_f32_16x16x32_bf16 v[4:7], v[168:171], v[176:179], v[4:7]
	v_mfma_f32_16x16x32_bf16 v[32:35], v[160:163], v[184:187], v[32:35]
	v_mfma_f32_16x16x32_bf16 v[0:3], v[168:171], v[184:187], v[0:3]
	v_mfma_f32_16x16x32_bf16 v[108:111], v[164:167], v[204:207], v[64:67]
	v_mfma_f32_16x16x32_bf16 v[64:67], v[168:171], v[200:203], v[100:103]
	v_mfma_f32_16x16x32_bf16 v[36:39], v[164:167], v[180:183], v[36:39]
	v_mfma_f32_16x16x32_bf16 v[4:7], v[172:175], v[180:183], v[4:7]
	v_mfma_f32_16x16x32_bf16 v[32:35], v[164:167], v[188:191], v[32:35]
	v_mfma_f32_16x16x32_bf16 v[0:3], v[172:175], v[188:191], v[0:3]
	v_mfma_f32_16x16x32_bf16 v[100:103], v[172:175], v[204:207], v[64:67]
	s_setprio 0
	s_barrier
	s_add_i32 s96, s96, 2
	s_add_u32 s94, s94, 0x100
	s_addc_u32 s95, s95, 0
	s_cmp_gt_u32 s96, 13
	s_mov_b64 s[62:63], s[64:65]
	s_cbranch_scc0 .LBB0_882
	s_and_b64 vcc, exec, s[18:19]
	s_cbranch_vccz .LBB0_885
	s_barrier

.LBB0_893:
	s_or_b64 exec, exec, s[58:59]
	v_lshlrev_b32_e32 v232, 2, v237
	v_mov_b32_e32 v233, 0
	v_add_u32_e32 v232, 0x22c00, v232
	ds_read_b128 v[106:109], v232 offset:512
	ds_read_b128 v[114:117], v232 offset:1024
	ds_read_b128 v[110:113], v232 offset:1536
	ds_read_b128 v[118:121], v232 offset:2048
	ds_read_b128 v[122:125], v232 offset:2560
	ds_read_b128 v[126:129], v232 offset:3584
	ds_read_b128 v[130:133], v232 offset:3072
	ds_read_b128 v[102:105], v232 offset:0
	v_mov_b32_dpp v222, v206 row_shr:1 row_mask:0xf bank_mask:0xf bound_ctrl:1
	v_mov_b32_dpp v226, v214 row_shr:1 row_mask:0xf bank_mask:0xf bound_ctrl:1
	v_mov_b32_dpp v216, v200 row_shr:1 row_mask:0xf bank_mask:0xf bound_ctrl:1
	v_mov_b32_dpp v218, v210 row_shr:1 row_mask:0xf bank_mask:0xf bound_ctrl:1
	v_mov_b32_dpp v223, v207 row_shr:1 row_mask:0xf bank_mask:0xf bound_ctrl:1
	v_mov_b32_dpp v227, v215 row_shr:1 row_mask:0xf bank_mask:0xf bound_ctrl:1
	v_mov_b32_dpp v217, v201 row_shr:1 row_mask:0xf bank_mask:0xf bound_ctrl:1
	v_mov_b32_dpp v219, v211 row_shr:1 row_mask:0xf bank_mask:0xf bound_ctrl:1
	v_mov_b32_dpp v228, v204 row_shr:1 row_mask:0xf bank_mask:0xf bound_ctrl:1
	v_mov_b32_dpp v230, v212 row_shr:1 row_mask:0xf bank_mask:0xf bound_ctrl:1
	v_mov_b32_dpp v220, v202 row_shr:1 row_mask:0xf bank_mask:0xf bound_ctrl:1
	v_mov_b32_dpp v224, v208 row_shr:1 row_mask:0xf bank_mask:0xf bound_ctrl:1
	v_mov_b32_dpp v229, v205 row_shr:1 row_mask:0xf bank_mask:0xf bound_ctrl:1
	v_mov_b32_dpp v231, v213 row_shr:1 row_mask:0xf bank_mask:0xf bound_ctrl:1
	v_mov_b32_dpp v221, v203 row_shr:1 row_mask:0xf bank_mask:0xf bound_ctrl:1
	v_mov_b32_dpp v225, v209 row_shr:1 row_mask:0xf bank_mask:0xf bound_ctrl:1
	s_waitcnt lgkmcnt(4)
	ds_read_b128 v[82:85], v232 offset:1040
	ds_read_b128 v[86:89], v232 offset:2064
	ds_read_b128 v[90:93], v232 offset:2576
	ds_read_b128 v[94:97], v232 offset:3600
	ds_read_b128 v[78:81], v232 offset:1552
	ds_read_b128 v[74:77], v232 offset:528
	ds_read_b128 v[70:73], v232 offset:16
	ds_read_b128 v[98:101], v232 offset:3088
	v_pk_mul_f32 v[46:47], v[46:47], v[68:69] op_sel:[0,1]
	v_pk_mul_f32 v[252:253], v[32:33], v[68:69] op_sel:[0,1]
	s_waitcnt lgkmcnt(0)
	v_pk_fma_f32 v[32:33], v[204:205], v[108:109], v[112:113]
	v_mov_b32_e32 v232, v67
	v_pk_fma_f32 v[32:33], v[46:47], v[104:105], v[32:33]
	v_pk_mul_f32 v[244:245], v[54:55], v[68:69] op_sel_hi:[1,0]
	v_pk_fma_f32 v[32:33], v[212:213], v[116:117], v[32:33]
	v_pk_mul_f32 v[54:55], v[48:49], v[66:67] op_sel_hi:[1,0]
	v_pk_mul_f32 v[48:49], v[42:43], v[232:233] op_sel_hi:[1,0]
	v_exp_f32_e32 v42, v32
	v_exp_f32_e32 v43, v33
	v_pk_mul_f32 v[44:45], v[44:45], v[68:69] op_sel:[0,1]
	v_pk_mul_f32 v[250:251], v[34:35], v[68:69] op_sel:[0,1]
	v_pk_fma_f32 v[34:35], v[206:207], v[106:107], v[110:111]
	v_add_f32_e32 v42, 1.0, v42
	v_pk_fma_f32 v[34:35], v[44:45], v[102:103], v[34:35]
	v_add_f32_e32 v43, 1.0, v43
	v_pk_fma_f32 v[34:35], v[214:215], v[114:115], v[34:35]
	v_pk_mul_f32 v[242:243], v[52:53], v[68:69] op_sel_hi:[1,0]
	v_pk_mul_f32 v[52:53], v[50:51], v[66:67] op_sel_hi:[1,0]
	v_pk_mul_f32 v[50:51], v[40:41], v[232:233] op_sel_hi:[1,0]
	v_rcp_f32_e32 v42, v42
	v_rcp_f32_e32 v43, v43
	v_pk_mul_f32 v[248:249], v[36:37], v[68:69] op_sel_hi:[1,0]
	v_pk_fma_f32 v[36:37], v[202:203], v[124:125], v[128:129]
	v_exp_f32_e32 v40, v34
	v_exp_f32_e32 v41, v35
	v_pk_fma_f32 v[36:37], v[250:251], v[120:121], v[36:37]
	v_pk_mul_f32 v[32:33], v[32:33], v[42:43]
	v_pk_fma_f32 v[36:37], v[208:209], v[132:133], v[36:37]
	v_add_f32_e32 v40, 1.0, v40
	v_add_f32_e32 v41, 1.0, v41
	v_pk_mul_f32 v[32:33], v[32:33], v[36:37]
	v_pk_fma_f32 v[36:37], v[44:45], v[106:107], v[110:111]
	v_rcp_f32_e32 v40, v40
	v_rcp_f32_e32 v41, v41
	v_pk_fma_f32 v[36:37], v[242:243], v[102:103], v[36:37]
	v_pk_mul_f32 v[246:247], v[38:39], v[68:69] op_sel_hi:[1,0]
	v_pk_fma_f32 v[38:39], v[200:201], v[122:123], v[126:127]
	v_pk_fma_f32 v[36:37], v[206:207], v[114:115], v[36:37]
	v_pk_fma_f32 v[38:39], v[252:253], v[118:119], v[38:39]
	v_pk_mul_f32 v[62:63], v[62:63], v[66:67] op_sel_hi:[1,0]
	v_pk_mul_f32 v[60:61], v[60:61], v[66:67] op_sel_hi:[1,0]
	v_pk_fma_f32 v[38:39], v[210:211], v[130:131], v[38:39]
	v_pk_mul_f32 v[34:35], v[34:35], v[40:41]
	v_exp_f32_e32 v67, v36
	v_pk_mul_f32 v[34:35], v[34:35], v[38:39]
	v_pk_fma_f32 v[38:39], v[46:47], v[108:109], v[112:113]
	v_exp_f32_e32 v153, v37
	v_pk_fma_f32 v[38:39], v[244:245], v[104:105], v[38:39]
	v_pk_fma_f32 v[42:43], v[252:253], v[122:123], v[126:127]
	v_pk_fma_f32 v[38:39], v[204:205], v[116:117], v[38:39]
	v_pk_fma_f32 v[42:43], v[248:249], v[118:119], v[42:43]
	v_add_f32_e32 v67, 1.0, v67
	v_pk_fma_f32 v[40:41], v[250:251], v[124:125], v[128:129]
	v_pk_fma_f32 v[42:43], v[200:201], v[130:131], v[42:43]
	v_rcp_f32_e32 v200, v67
	v_add_f32_e32 v67, 1.0, v153
	v_pk_fma_f32 v[40:41], v[246:247], v[120:121], v[40:41]
	v_exp_f32_e32 v153, v38
	v_pk_fma_f32 v[40:41], v[202:203], v[132:133], v[40:41]
	v_exp_f32_e32 v203, v39
	v_rcp_f32_e32 v201, v67
	v_add_f32_e32 v67, 1.0, v153
	v_rcp_f32_e32 v202, v67
	v_add_f32_e32 v67, 1.0, v203
	v_rcp_f32_e32 v203, v67
	v_pk_mul_f32 v[200:201], v[36:37], v[200:201]
	v_pk_mul_f32 v[56:57], v[56:57], v[232:233] op_sel_hi:[1,0]
	v_pk_mul_f32 v[36:37], v[38:39], v[202:203]
	v_pk_mul_f32 v[36:37], v[36:37], v[40:41]
	v_pk_fma_f32 v[40:41], v[242:243], v[106:107], v[110:111]
	v_pk_mul_f32 v[58:59], v[58:59], v[232:233] op_sel_hi:[1,0]
	v_pk_fma_f32 v[40:41], v[56:57], v[102:103], v[40:41]
	v_pk_mul_f32 v[38:39], v[200:201], v[42:43]
	v_pk_fma_f32 v[40:41], v[44:45], v[114:115], v[40:41]
	v_pk_fma_f32 v[42:43], v[244:245], v[108:109], v[112:113]
	v_pk_fma_f32 v[42:43], v[58:59], v[104:105], v[42:43]
	v_exp_f32_e32 v67, v40
	v_pk_fma_f32 v[42:43], v[46:47], v[116:117], v[42:43]
	v_pk_fma_f32 v[44:45], v[248:249], v[122:123], v[126:127]
	v_add_f32_e32 v67, 1.0, v67
	v_rcp_f32_e32 v200, v67
	v_exp_f32_e32 v153, v42
	v_exp_f32_e32 v67, v41
	v_exp_f32_e32 v201, v43
	v_add_f32_e32 v153, 1.0, v153
	v_rcp_f32_e32 v202, v153
	v_add_f32_e32 v67, 1.0, v67
	v_add_f32_e32 v153, 1.0, v201
	v_rcp_f32_e32 v203, v153
	v_rcp_f32_e32 v201, v67
	v_pk_fma_f32 v[46:47], v[246:247], v[124:125], v[128:129]
	v_pk_fma_f32 v[44:45], v[50:51], v[118:119], v[44:45]
	v_pk_fma_f32 v[46:47], v[48:49], v[120:121], v[46:47]
	v_pk_fma_f32 v[44:45], v[252:253], v[130:131], v[44:45]
	v_pk_fma_f32 v[46:47], v[250:251], v[132:133], v[46:47]
	v_pk_mul_f32 v[42:43], v[42:43], v[202:203]
	v_pk_mul_f32 v[200:201], v[40:41], v[200:201]
	v_pk_mul_f32 v[40:41], v[42:43], v[46:47]
	v_pk_mul_f32 v[42:43], v[200:201], v[44:45]
	v_pk_fma_f32 v[44:45], v[56:57], v[106:107], v[110:111]
	v_pk_fma_f32 v[46:47], v[58:59], v[108:109], v[112:113]
	v_pk_fma_f32 v[44:45], v[60:61], v[102:103], v[44:45]
	v_pk_fma_f32 v[46:47], v[62:63], v[104:105], v[46:47]
	v_pk_fma_f32 v[44:45], v[242:243], v[114:115], v[44:45]
	v_pk_fma_f32 v[46:47], v[244:245], v[116:117], v[46:47]
	v_exp_f32_e32 v67, v44
	v_exp_f32_e32 v153, v46
	v_add_f32_e32 v67, 1.0, v67
	v_rcp_f32_e32 v204, v67
	v_exp_f32_e32 v205, v47
	v_exp_f32_e32 v67, v45
	v_add_f32_e32 v153, 1.0, v153
	v_rcp_f32_e32 v206, v153
	v_add_f32_e32 v153, 1.0, v205
	v_add_f32_e32 v67, 1.0, v67
	v_rcp_f32_e32 v207, v153
	v_pk_fma_f32 v[202:203], v[48:49], v[124:125], v[128:129]
	v_rcp_f32_e32 v205, v67
	v_pk_fma_f32 v[202:203], v[52:53], v[120:121], v[202:203]
	v_pk_mul_f32 v[46:47], v[46:47], v[206:207]
	v_pk_fma_f32 v[202:203], v[246:247], v[132:133], v[202:203]
	v_pk_mul_f32 v[204:205], v[44:45], v[204:205]
	v_pk_fma_f32 v[200:201], v[50:51], v[122:123], v[126:127]
	v_pk_mul_f32 v[44:45], v[46:47], v[202:203]
	v_pk_fma_f32 v[202:203], v[60:61], v[106:107], v[110:111]
	v_pk_fma_f32 v[200:201], v[54:55], v[118:119], v[200:201]
	v_pk_fma_f32 v[202:203], v[198:199], v[102:103], v[202:203]
	v_pk_fma_f32 v[200:201], v[248:249], v[130:131], v[200:201]
	v_pk_fma_f32 v[56:57], v[56:57], v[114:115], v[202:203]
	v_pk_mul_f32 v[46:47], v[204:205], v[200:201]
	v_exp_f32_e32 v67, v56
	v_pk_fma_f32 v[200:201], v[62:63], v[108:109], v[112:113]
	v_pk_fma_f32 v[202:203], v[54:55], v[122:123], v[126:127]
	v_pk_fma_f32 v[200:201], v[194:195], v[104:105], v[200:201]
	v_add_f32_e32 v67, 1.0, v67
	v_pk_fma_f32 v[58:59], v[58:59], v[116:117], v[200:201]
	v_pk_fma_f32 v[200:201], v[52:53], v[124:125], v[128:129]
	v_pk_fma_f32 v[200:201], v[196:197], v[120:121], v[200:201]
	v_pk_fma_f32 v[48:49], v[48:49], v[132:133], v[200:201]
	v_rcp_f32_e32 v200, v67
	v_exp_f32_e32 v67, v57
	v_exp_f32_e32 v153, v58
	v_exp_f32_e32 v201, v59
	v_pk_fma_f32 v[202:203], v[192:193], v[118:119], v[202:203]
	v_add_f32_e32 v67, 1.0, v67
	v_add_f32_e32 v153, 1.0, v153
	v_pk_fma_f32 v[50:51], v[50:51], v[130:131], v[202:203]
	v_rcp_f32_e32 v202, v153
	v_add_f32_e32 v153, 1.0, v201
	v_rcp_f32_e32 v201, v67
	v_rcp_f32_e32 v203, v153
	v_pk_mul_f32 v[56:57], v[56:57], v[200:201]
	s_andn2_b64 vcc, exec, s[6:7]
	v_pk_mul_f32 v[50:51], v[56:57], v[50:51]
	v_pk_fma_f32 v[56:57], v[194:195], v[108:109], v[112:113]
	v_pk_mul_f32 v[58:59], v[58:59], v[202:203]
	v_pk_fma_f32 v[56:57], v[186:187], v[104:105], v[56:57]
	v_pk_mul_f32 v[48:49], v[58:59], v[48:49]
	v_pk_fma_f32 v[56:57], v[62:63], v[116:117], v[56:57]
	v_pk_fma_f32 v[62:63], v[192:193], v[122:123], v[126:127]
	v_pk_fma_f32 v[62:63], v[184:185], v[118:119], v[62:63]
	v_pk_fma_f32 v[58:59], v[198:199], v[106:107], v[110:111]
	v_pk_fma_f32 v[54:55], v[54:55], v[130:131], v[62:63]
	v_exp_f32_e32 v62, v56
	v_exp_f32_e32 v63, v57
	v_pk_fma_f32 v[58:59], v[190:191], v[102:103], v[58:59]
	v_pk_fma_f32 v[58:59], v[60:61], v[114:115], v[58:59]
	v_pk_fma_f32 v[60:61], v[196:197], v[124:125], v[128:129]
	v_pk_fma_f32 v[60:61], v[188:189], v[120:121], v[60:61]
	v_add_f32_e32 v62, 1.0, v62
	v_add_f32_e32 v63, 1.0, v63
	v_pk_fma_f32 v[52:53], v[52:53], v[132:133], v[60:61]
	v_rcp_f32_e32 v62, v62
	v_rcp_f32_e32 v63, v63
	v_exp_f32_e32 v67, v58
	v_exp_f32_e32 v61, v59
	v_pk_mul_f32 v[56:57], v[56:57], v[62:63]
	v_add_f32_e32 v60, 1.0, v67
	v_add_f32_e32 v61, 1.0, v61
	v_pk_mul_f32 v[52:53], v[56:57], v[52:53]
	v_pk_fma_f32 v[56:57], v[102:103], v[226:227], v[110:111]
	v_rcp_f32_e32 v60, v60
	v_rcp_f32_e32 v61, v61
	v_pk_fma_f32 v[56:57], v[190:191], v[106:107], v[56:57]
	v_pk_fma_f32 v[62:63], v[118:119], v[218:219], v[126:127]
	v_pk_fma_f32 v[56:57], v[198:199], v[114:115], v[56:57]
	v_pk_mul_f32 v[58:59], v[58:59], v[60:61]
	v_pk_mul_f32 v[54:55], v[58:59], v[54:55]
	v_exp_f32_e32 v67, v56
	v_pk_fma_f32 v[58:59], v[104:105], v[230:231], v[112:113]
	v_exp_f32_e32 v153, v57
	v_pk_fma_f32 v[58:59], v[186:187], v[108:109], v[58:59]
	v_pk_fma_f32 v[62:63], v[184:185], v[122:123], v[62:63]
	v_pk_fma_f32 v[58:59], v[194:195], v[116:117], v[58:59]
	v_add_f32_e32 v67, 1.0, v67
	v_pk_fma_f32 v[62:63], v[192:193], v[130:131], v[62:63]
	v_rcp_f32_e32 v192, v67
	v_add_f32_e32 v67, 1.0, v153
	v_exp_f32_e32 v153, v58
	v_exp_f32_e32 v195, v59
	v_rcp_f32_e32 v193, v67
	v_add_f32_e32 v67, 1.0, v153
	v_rcp_f32_e32 v194, v67
	v_add_f32_e32 v67, 1.0, v195
	v_rcp_f32_e32 v195, v67
	v_pk_fma_f32 v[60:61], v[120:121], v[224:225], v[128:129]
	v_pk_mul_f32 v[192:193], v[56:57], v[192:193]
	v_pk_fma_f32 v[60:61], v[188:189], v[124:125], v[60:61]
	v_pk_mul_f32 v[56:57], v[58:59], v[194:195]
	v_pk_fma_f32 v[60:61], v[196:197], v[132:133], v[60:61]
	v_pk_mul_f32 v[58:59], v[62:63], v[192:193]
	v_pk_mul_f32 v[56:57], v[60:61], v[56:57]
	v_pk_fma_f32 v[60:61], v[106:107], v[226:227], v[110:111]
	v_pk_fma_f32 v[62:63], v[108:109], v[230:231], v[112:113]
	v_pk_fma_f32 v[60:61], v[102:103], v[222:223], v[60:61]
	v_pk_fma_f32 v[62:63], v[104:105], v[228:229], v[62:63]
	v_pk_fma_f32 v[60:61], v[190:191], v[114:115], v[60:61]
	v_pk_fma_f32 v[104:105], v[122:123], v[218:219], v[126:127]
	v_pk_fma_f32 v[104:105], v[118:119], v[216:217], v[104:105]
	v_pk_fma_f32 v[102:103], v[124:125], v[224:225], v[128:129]
	v_exp_f32_e32 v67, v60
	v_pk_fma_f32 v[104:105], v[184:185], v[130:131], v[104:105]
	v_pk_fma_f32 v[102:103], v[120:121], v[220:221], v[102:103]
	v_exp_f32_e32 v107, v61
	v_pk_mul_f32 v[120:121], v[14:15], v[68:69] op_sel:[0,1]
	v_pk_mul_f32 v[126:127], v[0:1], v[68:69] op_sel:[0,1]
	v_pk_fma_f32 v[0:1], v[172:173], v[76:77], v[80:81]
	v_pk_mul_f32 v[122:123], v[12:13], v[68:69] op_sel:[0,1]
	v_pk_mul_f32 v[124:125], v[2:3], v[68:69] op_sel:[0,1]
	v_pk_fma_f32 v[2:3], v[174:175], v[74:75], v[78:79]
	v_pk_fma_f32 v[0:1], v[120:121], v[72:73], v[0:1]
	v_pk_fma_f32 v[62:63], v[186:187], v[116:117], v[62:63]
	v_pk_fma_f32 v[2:3], v[122:123], v[70:71], v[2:3]
	v_pk_fma_f32 v[0:1], v[180:181], v[84:85], v[0:1]
	v_add_f32_e32 v67, 1.0, v67
	v_pk_fma_f32 v[2:3], v[182:183], v[82:83], v[2:3]
	v_rcp_f32_e32 v106, v67
	v_add_f32_e32 v67, 1.0, v107
	v_pk_mul_f32 v[110:111], v[26:27], v[232:233] op_sel_hi:[1,0]
	v_exp_f32_e32 v108, v62
	v_pk_mul_f32 v[112:113], v[24:25], v[232:233] op_sel_hi:[1,0]
	v_exp_f32_e32 v26, v0
	v_exp_f32_e32 v27, v1
	v_exp_f32_e32 v109, v63
	v_exp_f32_e32 v24, v2
	v_exp_f32_e32 v25, v3
	v_rcp_f32_e32 v107, v67
	v_add_f32_e32 v67, 1.0, v108
	v_add_f32_e32 v26, 1.0, v26
	v_add_f32_e32 v27, 1.0, v27
	v_rcp_f32_e32 v108, v67
	v_add_f32_e32 v67, 1.0, v109
	v_add_f32_e32 v24, 1.0, v24
	v_add_f32_e32 v25, 1.0, v25
	v_rcp_f32_e32 v26, v26
	v_rcp_f32_e32 v27, v27
	v_rcp_f32_e32 v109, v67
	v_pk_mul_f32 v[118:119], v[4:5], v[68:69] op_sel_hi:[1,0]
	v_pk_fma_f32 v[4:5], v[170:171], v[92:93], v[96:97]
	v_rcp_f32_e32 v24, v24
	v_rcp_f32_e32 v25, v25
	v_pk_mul_f32 v[116:117], v[6:7], v[68:69] op_sel_hi:[1,0]
	v_pk_fma_f32 v[6:7], v[168:169], v[90:91], v[94:95]
	v_pk_fma_f32 v[4:5], v[124:125], v[88:89], v[4:5]
	v_pk_fma_f32 v[6:7], v[126:127], v[86:87], v[6:7]
	v_pk_fma_f32 v[4:5], v[176:177], v[100:101], v[4:5]
	v_pk_mul_f32 v[106:107], v[60:61], v[106:107]
	v_pk_fma_f32 v[6:7], v[178:179], v[98:99], v[6:7]
	v_pk_mul_f32 v[0:1], v[0:1], v[26:27]
	v_pk_mul_f32 v[60:61], v[62:63], v[108:109]
	v_pk_mul_f32 v[62:63], v[104:105], v[106:107]
	v_pk_mul_f32 v[104:105], v[20:21], v[68:69] op_sel_hi:[1,0]
	v_pk_mul_f32 v[2:3], v[2:3], v[24:25]
	v_pk_mul_f32 v[0:1], v[0:1], v[4:5]
	v_pk_fma_f32 v[4:5], v[122:123], v[74:75], v[78:79]
	v_pk_mul_f32 v[114:115], v[22:23], v[68:69] op_sel_hi:[1,0]
	v_pk_mul_f32 v[2:3], v[2:3], v[6:7]
	v_pk_fma_f32 v[6:7], v[120:121], v[76:77], v[80:81]
	v_pk_fma_f32 v[4:5], v[104:105], v[70:71], v[4:5]
	v_pk_fma_f32 v[102:103], v[188:189], v[132:133], v[102:103]
	v_pk_fma_f32 v[6:7], v[114:115], v[72:73], v[6:7]
	v_pk_fma_f32 v[4:5], v[174:175], v[82:83], v[4:5]
	v_pk_fma_f32 v[6:7], v[172:173], v[84:85], v[6:7]
	v_pk_mul_f32 v[60:61], v[102:103], v[60:61]
	v_pk_mul_f32 v[68:69], v[30:31], v[66:67] op_sel_hi:[1,0]
	v_pk_mul_f32 v[102:103], v[28:29], v[66:67] op_sel_hi:[1,0]
	v_pk_mul_f32 v[28:29], v[18:19], v[66:67] op_sel_hi:[1,0]
	v_pk_mul_f32 v[30:31], v[16:17], v[66:67] op_sel_hi:[1,0]
	v_exp_f32_e32 v66, v4
	v_exp_f32_e32 v67, v5
	v_exp_f32_e32 v128, v6
	v_exp_f32_e32 v129, v7
	v_add_f32_e32 v66, 1.0, v66
	v_add_f32_e32 v67, 1.0, v67
	v_rcp_f32_e32 v66, v66
	v_rcp_f32_e32 v67, v67
	v_add_f32_e32 v128, 1.0, v128
	v_add_f32_e32 v129, 1.0, v129
	v_pk_fma_f32 v[26:27], v[126:127], v[90:91], v[94:95]
	v_rcp_f32_e32 v128, v128
	v_rcp_f32_e32 v129, v129
	v_pk_fma_f32 v[24:25], v[124:125], v[92:93], v[96:97]
	v_pk_fma_f32 v[26:27], v[118:119], v[86:87], v[26:27]
	v_pk_fma_f32 v[24:25], v[116:117], v[88:89], v[24:25]
	v_pk_fma_f32 v[26:27], v[168:169], v[98:99], v[26:27]
	v_pk_fma_f32 v[24:25], v[170:171], v[100:101], v[24:25]
	v_pk_mul_f32 v[66:67], v[4:5], v[66:67]
	v_pk_mul_f32 v[4:5], v[6:7], v[128:129]
	v_pk_mul_f32 v[6:7], v[66:67], v[26:27]
	v_pk_fma_f32 v[26:27], v[114:115], v[76:77], v[80:81]
	v_pk_mul_f32 v[4:5], v[4:5], v[24:25]
	v_pk_fma_f32 v[24:25], v[104:105], v[74:75], v[78:79]
	v_pk_fma_f32 v[26:27], v[110:111], v[72:73], v[26:27]
	v_pk_mul_f32 v[106:107], v[10:11], v[232:233] op_sel_hi:[1,0]
	v_pk_fma_f32 v[24:25], v[112:113], v[70:71], v[24:25]
	v_pk_fma_f32 v[26:27], v[120:121], v[84:85], v[26:27]
	v_pk_fma_f32 v[120:121], v[116:117], v[92:93], v[96:97]
	v_pk_fma_f32 v[24:25], v[122:123], v[82:83], v[24:25]
	v_pk_fma_f32 v[120:121], v[106:107], v[88:89], v[120:121]
	v_pk_fma_f32 v[120:121], v[124:125], v[100:101], v[120:121]
	v_exp_f32_e32 v124, v26
	v_exp_f32_e32 v125, v27
	v_exp_f32_e32 v122, v24
	v_exp_f32_e32 v123, v25
	v_add_f32_e32 v124, 1.0, v124
	v_add_f32_e32 v125, 1.0, v125
	v_add_f32_e32 v122, 1.0, v122
	v_add_f32_e32 v123, 1.0, v123
	v_rcp_f32_e32 v124, v124
	v_rcp_f32_e32 v125, v125
	v_rcp_f32_e32 v122, v122
	v_rcp_f32_e32 v123, v123
	v_pk_mul_f32 v[108:109], v[8:9], v[232:233] op_sel_hi:[1,0]
	v_pk_fma_f32 v[66:67], v[118:119], v[90:91], v[94:95]
	v_pk_fma_f32 v[66:67], v[108:109], v[86:87], v[66:67]
	v_pk_mul_f32 v[26:27], v[26:27], v[124:125]
	v_pk_fma_f32 v[66:67], v[126:127], v[98:99], v[66:67]
	v_pk_mul_f32 v[122:123], v[24:25], v[122:123]
	v_pk_mul_f32 v[24:25], v[26:27], v[120:121]
	v_pk_mul_f32 v[120:121], v[110:111], v[76:77]
	v_pk_mul_f32 v[26:27], v[122:123], v[66:67]
	v_pk_fma_f32 v[66:67], v[112:113], v[74:75], v[78:79]
	v_pk_fma_f32 v[120:121], v[68:69], v[72:73], v[120:121]
	v_pk_fma_f32 v[66:67], v[102:103], v[70:71], v[66:67]
	v_pk_fma_f32 v[114:115], v[114:115], v[84:85], v[120:121]
	v_pk_fma_f32 v[66:67], v[104:105], v[82:83], v[66:67]
	v_pk_add_f32 v[104:105], v[114:115], v[80:81]
	v_pk_fma_f32 v[114:115], v[108:109], v[90:91], v[94:95]
	v_pk_fma_f32 v[120:121], v[106:107], v[92:93], v[96:97]
	v_pk_fma_f32 v[120:121], v[28:29], v[88:89], v[120:121]
	v_pk_fma_f32 v[114:115], v[30:31], v[86:87], v[114:115]
	v_pk_fma_f32 v[116:117], v[116:117], v[100:101], v[120:121]
	v_pk_fma_f32 v[114:115], v[118:119], v[98:99], v[114:115]
	v_exp_f32_e32 v122, v66
	v_exp_f32_e32 v119, v67
	v_exp_f32_e32 v120, v104
	v_exp_f32_e32 v121, v105
	v_add_f32_e32 v118, 1.0, v122
	v_add_f32_e32 v119, 1.0, v119
	v_add_f32_e32 v120, 1.0, v120
	v_add_f32_e32 v121, 1.0, v121
	v_rcp_f32_e32 v118, v118
	v_rcp_f32_e32 v120, v120
	v_rcp_f32_e32 v121, v121
	v_rcp_f32_e32 v119, v119
	v_pk_mul_f32 v[104:105], v[104:105], v[120:121]
	v_pk_mul_f32 v[118:119], v[66:67], v[118:119]
	v_pk_mul_f32 v[66:67], v[104:105], v[116:117]
	v_pk_mul_f32 v[104:105], v[118:119], v[114:115]
	v_pk_fma_f32 v[114:115], v[68:69], v[76:77], v[80:81]
	v_pk_fma_f32 v[116:117], v[102:103], v[74:75], v[78:79]
	v_pk_fma_f32 v[114:115], v[162:163], v[72:73], v[114:115]
	v_pk_fma_f32 v[116:117], v[166:167], v[70:71], v[116:117]
	v_pk_fma_f32 v[110:111], v[110:111], v[84:85], v[114:115]
	v_pk_fma_f32 v[112:113], v[112:113], v[82:83], v[116:117]
	v_pk_fma_f32 v[114:115], v[28:29], v[92:93], v[96:97]
	v_pk_fma_f32 v[116:117], v[30:31], v[90:91], v[94:95]
	v_pk_fma_f32 v[116:117], v[64:65], v[86:87], v[116:117]
	v_pk_fma_f32 v[114:115], v[164:165], v[88:89], v[114:115]
	v_pk_fma_f32 v[106:107], v[106:107], v[100:101], v[114:115]
	v_pk_fma_f32 v[108:109], v[108:109], v[98:99], v[116:117]
	v_exp_f32_e32 v118, v112
	v_exp_f32_e32 v115, v113
	v_exp_f32_e32 v116, v110
	v_exp_f32_e32 v117, v111
	v_add_f32_e32 v114, 1.0, v118
	v_add_f32_e32 v115, 1.0, v115
	v_add_f32_e32 v116, 1.0, v116
	v_add_f32_e32 v117, 1.0, v117
	v_rcp_f32_e32 v114, v114
	v_rcp_f32_e32 v116, v116
	v_rcp_f32_e32 v117, v117
	v_rcp_f32_e32 v115, v115
	v_pk_mul_f32 v[110:111], v[110:111], v[116:117]
	v_pk_mul_f32 v[112:113], v[112:113], v[114:115]
	v_pk_mul_f32 v[106:107], v[110:111], v[106:107]
	v_pk_mul_f32 v[108:109], v[112:113], v[108:109]
	v_pk_fma_f32 v[110:111], v[162:163], v[76:77], v[80:81]
	v_pk_fma_f32 v[112:113], v[166:167], v[74:75], v[78:79]
	v_pk_fma_f32 v[110:111], v[156:157], v[72:73], v[110:111]
	v_pk_fma_f32 v[112:113], v[160:161], v[70:71], v[112:113]
	v_pk_fma_f32 v[68:69], v[68:69], v[84:85], v[110:111]
	v_pk_fma_f32 v[102:103], v[102:103], v[82:83], v[112:113]
	v_pk_fma_f32 v[110:111], v[164:165], v[92:93], v[96:97]
	v_pk_fma_f32 v[112:113], v[64:65], v[90:91], v[94:95]
	v_pk_fma_f32 v[112:113], v[134:135], v[86:87], v[112:113]
	v_pk_fma_f32 v[110:111], v[158:159], v[88:89], v[110:111]
	v_pk_fma_f32 v[28:29], v[28:29], v[100:101], v[110:111]
	v_pk_fma_f32 v[30:31], v[30:31], v[98:99], v[112:113]
	v_exp_f32_e32 v114, v102
	v_exp_f32_e32 v111, v103
	v_exp_f32_e32 v112, v68
	v_exp_f32_e32 v113, v69
	v_add_f32_e32 v110, 1.0, v114
	v_add_f32_e32 v111, 1.0, v111
	v_add_f32_e32 v112, 1.0, v112
	v_add_f32_e32 v113, 1.0, v113
	v_rcp_f32_e32 v110, v110
	v_rcp_f32_e32 v112, v112
	v_rcp_f32_e32 v113, v113
	v_rcp_f32_e32 v111, v111
	v_mov_b32_dpp v18, v182 row_shr:1 row_mask:0xf bank_mask:0xf bound_ctrl:1
	v_mov_b32_dpp v19, v183 row_shr:1 row_mask:0xf bank_mask:0xf bound_ctrl:1
	v_mov_b32_dpp v22, v180 row_shr:1 row_mask:0xf bank_mask:0xf bound_ctrl:1
	v_mov_b32_dpp v23, v181 row_shr:1 row_mask:0xf bank_mask:0xf bound_ctrl:1
	v_pk_mul_f32 v[68:69], v[68:69], v[112:113]
	v_pk_mul_f32 v[102:103], v[102:103], v[110:111]
	v_mov_b32_dpp v14, v174 row_shr:1 row_mask:0xf bank_mask:0xf bound_ctrl:1
	v_mov_b32_dpp v15, v175 row_shr:1 row_mask:0xf bank_mask:0xf bound_ctrl:1
	v_mov_b32_dpp v20, v172 row_shr:1 row_mask:0xf bank_mask:0xf bound_ctrl:1
	v_mov_b32_dpp v21, v173 row_shr:1 row_mask:0xf bank_mask:0xf bound_ctrl:1
	v_pk_mul_f32 v[28:29], v[68:69], v[28:29]
	v_pk_mul_f32 v[30:31], v[102:103], v[30:31]
	v_pk_fma_f32 v[68:69], v[70:71], v[18:19], v[78:79]
	v_pk_fma_f32 v[102:103], v[72:73], v[22:23], v[80:81]
	v_pk_fma_f32 v[18:19], v[74:75], v[18:19], v[78:79]
	v_pk_fma_f32 v[22:23], v[76:77], v[22:23], v[80:81]
	v_pk_fma_f32 v[14:15], v[70:71], v[14:15], v[18:19]
	v_pk_fma_f32 v[20:21], v[72:73], v[20:21], v[22:23]
	v_mov_b32_dpp v10, v178 row_shr:1 row_mask:0xf bank_mask:0xf bound_ctrl:1
	v_mov_b32_dpp v11, v179 row_shr:1 row_mask:0xf bank_mask:0xf bound_ctrl:1
	v_mov_b32_dpp v16, v176 row_shr:1 row_mask:0xf bank_mask:0xf bound_ctrl:1
	v_mov_b32_dpp v17, v177 row_shr:1 row_mask:0xf bank_mask:0xf bound_ctrl:1
	v_pk_fma_f32 v[68:69], v[160:161], v[74:75], v[68:69]
	v_pk_fma_f32 v[14:15], v[160:161], v[82:83], v[14:15]
	v_pk_fma_f32 v[18:19], v[156:157], v[84:85], v[20:21]
	v_mov_b32_dpp v8, v168 row_shr:1 row_mask:0xf bank_mask:0xf bound_ctrl:1
	v_mov_b32_dpp v9, v169 row_shr:1 row_mask:0xf bank_mask:0xf bound_ctrl:1
	v_mov_b32_dpp v12, v170 row_shr:1 row_mask:0xf bank_mask:0xf bound_ctrl:1
	v_mov_b32_dpp v13, v171 row_shr:1 row_mask:0xf bank_mask:0xf bound_ctrl:1
	v_pk_fma_f32 v[68:69], v[166:167], v[82:83], v[68:69]
	v_pk_fma_f32 v[110:111], v[88:89], v[16:17], v[96:97]
	v_pk_fma_f32 v[112:113], v[86:87], v[10:11], v[94:95]
	v_pk_fma_f32 v[16:17], v[92:93], v[16:17], v[96:97]
	v_pk_fma_f32 v[10:11], v[90:91], v[10:11], v[94:95]
	v_pk_fma_f32 v[8:9], v[86:87], v[8:9], v[10:11]
	v_pk_fma_f32 v[10:11], v[88:89], v[12:13], v[16:17]
	v_exp_f32_e32 v12, v14
	v_exp_f32_e32 v13, v15
	v_exp_f32_e32 v16, v18
	v_exp_f32_e32 v17, v19
	v_exp_f32_e32 v114, v68
	v_exp_f32_e32 v115, v69
	v_pk_fma_f32 v[102:103], v[156:157], v[76:77], v[102:103]
	v_pk_fma_f32 v[112:113], v[134:135], v[90:91], v[112:113]
	v_pk_fma_f32 v[102:103], v[162:163], v[84:85], v[102:103]
	v_add_f32_e32 v12, 1.0, v12
	v_add_f32_e32 v13, 1.0, v13
	v_add_f32_e32 v16, 1.0, v16
	v_add_f32_e32 v17, 1.0, v17
	v_pk_fma_f32 v[64:65], v[64:65], v[98:99], v[112:113]
	v_add_f32_e32 v112, 1.0, v114
	v_add_f32_e32 v113, 1.0, v115
	v_rcp_f32_e32 v12, v12
	v_rcp_f32_e32 v13, v13
	v_rcp_f32_e32 v16, v16
	v_rcp_f32_e32 v17, v17
	v_exp_f32_e32 v114, v102
	v_exp_f32_e32 v115, v103
	v_pk_fma_f32 v[10:11], v[158:159], v[100:101], v[10:11]
	v_pk_fma_f32 v[8:9], v[134:135], v[98:99], v[8:9]
	v_pk_mul_f32 v[12:13], v[14:15], v[12:13]
	v_pk_mul_f32 v[14:15], v[18:19], v[16:17]
	v_add_f32_e32 v114, 1.0, v114
	v_add_f32_e32 v115, 1.0, v115
	v_pk_mul_f32 v[14:15], v[10:11], v[14:15]
	v_pk_mul_f32 v[10:11], v[8:9], v[12:13]
	v_mov_b64_e32 v[12:13], s[16:17]
	v_readfirstlane_b32 s62, v152
	v_readfirstlane_b32 s63, v154
	v_mbcnt_lo_u32_b32 v176, -1, 0
	v_mbcnt_hi_u32_b32 v176, -1, v176
	v_lshrrev_b32_e32 v177, 2, v176
	v_and_b32_e32 v178, 3, v176
	s_mul_i32 s62, s62, 0x1600
	s_lshl_b32 s63, s63, 1
	s_add_i32 s62, s62, s63
	v_mul_u32_u24_e32 v179, 0xb000, v177
	v_lshl_add_u32 v179, v178, 4, v179
	v_add_u32_e32 v179, s62, v179
	s_lshr_b32 s63, s33, 6
	s_mulk_i32 s63, 0x500
	s_add_i32 s63, s63, 0x20400
	v_mul_u32_u24_e32 v188, 0x50, v177
	v_lshl_add_u32 v188, v178, 4, v188
	v_add_u32_e32 v188, s63, v188
	v_and_b32_e32 v177, 15, v176
	v_lshrrev_b32_e32 v178, 4, v176
	v_mul_u32_u24_e32 v189, 0x50, v177
	v_lshl_add_u32 v189, v178, 4, v189
	v_add_u32_e32 v189, s63, v189
	v_rcp_f32_e32 v112, v112
	v_rcp_f32_e32 v113, v113
	v_rcp_f32_e32 v114, v114
	v_rcp_f32_e32 v115, v115
	v_cvt_pk_bf16_f32 v8, v62, v63
	v_cvt_pk_bf16_f32 v9, v60, v61
	v_cvt_pk_bf16_f32 v10, v10, v11
	v_cvt_pk_bf16_f32 v11, v14, v15
	v_mad_i64_i32 v[14:15], s[26:27], v152, s93, v[12:13]
	v_lshlrev_b64 v[16:17], 1, v[154:155]
	v_lshl_add_u64 v[14:15], v[14:15], 0, v[16:17]
	v_pk_fma_f32 v[110:111], v[158:159], v[92:93], v[110:111]
	ds_write_b128 v189, v[8:11]
	ds_read_b128 v[180:183], v188
	s_waitcnt lgkmcnt(0)
	global_store_dwordx4 v179, v[180:183], s[16:17]
	v_or_b32_e32 v14, 1, v152
	v_pk_fma_f32 v[110:111], v[164:165], v[100:101], v[110:111]
	v_mad_i64_i32 v[14:15], s[26:27], v14, s93, v[12:13]
	v_pk_mul_f32 v[68:69], v[68:69], v[112:113]
	v_pk_mul_f32 v[102:103], v[102:103], v[114:115]
	v_lshl_add_u64 v[14:15], v[14:15], 0, v[16:17]
	v_pk_mul_f32 v[102:103], v[110:111], v[102:103]
	v_pk_mul_f32 v[64:65], v[64:65], v[68:69]
	v_cvt_pk_bf16_f32 v8, v58, v59
	v_cvt_pk_bf16_f32 v9, v56, v57
	s_mov_b64 s[6:7], -1
	v_cvt_pk_bf16_f32 v10, v64, v65
	v_cvt_pk_bf16_f32 v11, v102, v103
	ds_write_b128 v189, v[8:11]
	ds_read_b128 v[184:187], v188
	v_add_u32_e32 v190, 0x1600, v179
	s_waitcnt lgkmcnt(0)
	global_store_dwordx4 v190, v[184:187], s[16:17]
	v_or_b32_e32 v14, 2, v152
	v_mad_i64_i32 v[14:15], s[26:27], v14, s93, v[12:13]
	v_lshl_add_u64 v[14:15], v[14:15], 0, v[16:17]
	v_cvt_pk_bf16_f32 v8, v54, v55
	v_cvt_pk_bf16_f32 v9, v52, v53
	v_cvt_pk_bf16_f32 v10, v30, v31
	v_cvt_pk_bf16_f32 v11, v28, v29
	ds_write_b128 v189, v[8:11]
	ds_read_b128 v[180:183], v188
	v_add_u32_e32 v190, 0x2c00, v179
	s_waitcnt lgkmcnt(0)
	global_store_dwordx4 v190, v[180:183], s[16:17]
	v_or_b32_e32 v14, 3, v152
	v_mad_i64_i32 v[14:15], s[26:27], v14, s93, v[12:13]
	v_lshl_add_u64 v[14:15], v[14:15], 0, v[16:17]
	v_cvt_pk_bf16_f32 v8, v50, v51
	v_cvt_pk_bf16_f32 v9, v48, v49
	v_cvt_pk_bf16_f32 v10, v108, v109
	v_cvt_pk_bf16_f32 v11, v106, v107
	ds_write_b128 v189, v[8:11]
	ds_read_b128 v[184:187], v188
	v_add_u32_e32 v190, 0x4200, v179
	s_waitcnt lgkmcnt(0)
	global_store_dwordx4 v190, v[184:187], s[16:17]
	v_or_b32_e32 v14, 4, v152
	v_mad_i64_i32 v[14:15], s[26:27], v14, s93, v[12:13]
	v_lshl_add_u64 v[14:15], v[14:15], 0, v[16:17]
	v_cvt_pk_bf16_f32 v8, v46, v47
	v_cvt_pk_bf16_f32 v9, v44, v45
	v_cvt_pk_bf16_f32 v10, v104, v105
	v_cvt_pk_bf16_f32 v11, v66, v67
	ds_write_b128 v189, v[8:11]
	ds_read_b128 v[180:183], v188
	v_add_u32_e32 v190, 0x5800, v179
	s_waitcnt lgkmcnt(0)
	global_store_dwordx4 v190, v[180:183], s[16:17]
	v_or_b32_e32 v14, 5, v152
	v_mad_i64_i32 v[14:15], s[26:27], v14, s93, v[12:13]
	v_cvt_pk_bf16_f32 v8, v42, v43
	v_cvt_pk_bf16_f32 v9, v40, v41
	v_cvt_pk_bf16_f32 v10, v26, v27
	v_cvt_pk_bf16_f32 v11, v24, v25
	v_lshl_add_u64 v[14:15], v[14:15], 0, v[16:17]
	ds_write_b128 v189, v[8:11]
	ds_read_b128 v[184:187], v188
	v_add_u32_e32 v190, 0x6e00, v179
	s_waitcnt lgkmcnt(0)
	global_store_dwordx4 v190, v[184:187], s[16:17]
	s_nop 1
	v_cvt_pk_bf16_f32 v8, v38, v39
	v_cvt_pk_bf16_f32 v9, v36, v37
	v_cvt_pk_bf16_f32 v10, v6, v7
	v_cvt_pk_bf16_f32 v11, v4, v5
	v_or_b32_e32 v4, 6, v152
	v_mad_i64_i32 v[4:5], s[26:27], v4, s93, v[12:13]
	v_lshl_add_u64 v[4:5], v[4:5], 0, v[16:17]
	ds_write_b128 v189, v[8:11]
	ds_read_b128 v[180:183], v188
	v_add_u32_e32 v190, 0x8400, v179
	s_waitcnt lgkmcnt(0)
	global_store_dwordx4 v190, v[180:183], s[16:17]
	v_cvt_pk_bf16_f32 v4, v34, v35
	v_cvt_pk_bf16_f32 v5, v32, v33
	v_cvt_pk_bf16_f32 v6, v2, v3
	v_cvt_pk_bf16_f32 v7, v0, v1
	v_or_b32_e32 v0, 7, v152
	v_mad_i64_i32 v[0:1], s[26:27], v0, s93, v[12:13]
	v_lshl_add_u64 v[0:1], v[0:1], 0, v[16:17]
	ds_write_b128 v189, v[4:7]
	ds_read_b128 v[184:187], v188
	v_add_u32_e32 v190, 0x9a00, v179
	s_waitcnt lgkmcnt(0)
	global_store_dwordx4 v190, v[184:187], s[16:17]
	s_cbranch_vccnz .LBB0_878
	s_andn2_b64 vcc, exec, s[0:1]
	s_cbranch_vccnz .LBB0_877
	s_barrier
	s_branch .LBB0_877
